# X46: gate|up K-loop - scalar pointer, LDS-slot, tile-switch and loop-counter code moved from the load segments into the MFMA shadow of the preceding MMA block; back edge is a bare branch
# speedup vs baseline: 1.0012x; 1.0010x over previous
; #define PG8_STAGE(bufoff, gbase, voff) do { _Pragma("unroll") for (int _i = 0; _i < 2; ++_i) \
;         __builtin_amdgcn_global_load_lds((const unsigned*)((const char*)(gbase) + (voff)[_i]), (PG8_LAS unsigned*)(lds + (bufoff) + ldsw + _i * 8192), 16, 0, 0); } while (0)
; #define PG8_LDA(dst, b, h) do { _Pragma("unroll") for (int m = 0; m < 4; ++m) _Pragma("unroll") for (int k = 0; k < 2; ++k) dst[m][k] = *(const PG8_LAS bf16x8*)(lds + PG8_SA(b, h) + aoff + m * 2048 + k * 1024); } while (0)
; #define PG8_LDB(dst, b, h) do { _Pragma("unroll") for (int n = 0; n < 2; ++n) _Pragma("unroll") for (int k = 0; k < 2; ++k) dst[n][k] = *(const PG8_LAS bf16x8*)(lds + PG8_SB(b, h) + boff + n * 2048 + k * 1024); } while (0)
; #define PG8_WAIT_V(n) asm volatile("s_waitcnt vmcnt(" #n ")" ::: "memory")
; #define PG8_WAIT_L(n) asm volatile("s_waitcnt lgkmcnt(" #n ")" ::: "memory")
; #define PG8_BAR __builtin_amdgcn_s_barrier()
; template <class Epi, class Sched, bool ALIGN_EPI = false, bool SP2 = false>
; __device__ __forceinline__ void gemm_phase(PG8_LAS unsigned char* lds, const Gemm g, const Sched& S, const Epi& E) {
;     ...
;         const bool has_next = S.next(ui + 1, nxt);
;         typename Epi::Pre pre; E.prefetch(pre, cur, wr, fr, lds, ui, wid, lane);
;         const char* nA = has_next ? (const char*)g.A + (size_t)nxt.pm * tstep : cA; const char* nB = has_next ? (const char*)g.Bt + (size_t)nxt.pn * tstep : cB;
;         for (int t = 0; t < nt; t += 2) {
;             const bool last = (t == nt - 2);
;             const char* a1 = cA + (size_t)(t + 1) * kstep;
;             const char* a2 = last ? nA : cA + (size_t)(t + 2) * kstep; const char* b2 = last ? nB : cB + (size_t)(t + 2) * kstep;
;             const char* a3 = a2 + kstep; const char* b3 = b2 + kstep;
;             if (last && has_next) S.a_ready(nxt);
;             if constexpr (SP2) {
;             PG8_LDB(B0, 0, 0); PG8_LDB(B1, 0, 1); PG8_SCHED; PG8_LDA(At, 0, 0); PG8_STAGE(PG8_SA(1, 1), a1 + hstep, voffA);
;             PG8_WAIT_V(8); PG8_WAIT_L(0); PG8_BAR; PG8_MMA(0, 0, At, B0); PG8_MMA(0, 1, At, B1); PG8_BAR; PG8_SCHED;
;             PG8_LDA(At, 0, 1); PG8_STAGE(PG8_SB(0, 0), b2, voffB); PG8_STAGE(PG8_SB(0, 1), b2 + hstep, voffB); PG8_STAGE(PG8_SA(0, 0), a2, voffA);
;             PG8_WAIT_V(8); PG8_WAIT_L(0); PG8_BAR; PG8_MMA(1, 0, At, B0); PG8_MMA(1, 1, At, B1); PG8_BAR; PG8_SCHED;
.LBB0_215:
	s_ashr_i32 s47, s46, 31
	s_lshl_b64 s[50:51], s[46:47], 20
	s_add_u32 s50, s96, s50
	s_addc_u32 s51, s97, s51
	s_and_b64 s[52:53], s[36:37], exec
	s_cselect_b32 s47, s51, s55
	s_cselect_b32 vcc_lo, s50, s54
	s_ashr_i32 s49, s48, 31
	s_lshl_b64 s[52:53], s[48:49], 20
	s_add_u32 s52, s61, s52
	s_addc_u32 s53, s64, s53
	s_and_b64 s[56:57], s[36:37], exec
	s_cselect_b32 s49, s53, s23
	s_cselect_b32 vcc_hi, s52, s22
	s_add_u32 s54, s54, 0x80080
	s_addc_u32 s55, s55, 0
	s_add_u32 s71, s22, 0x100
	s_addc_u32 s77, s23, 0
	s_mov_b32 s20, -2
	v_add_u32_e32 v152, 0x10000, v155
	v_add_u32_e32 v153, 0x14000, v155
	v_add_u32_e32 v192, 0x18000, v155
	v_add_u32_e32 v193, 0x1c000, v155
	s_add_u32 s22, s54, 0xfff80080
	s_addc_u32 s23, s55, -1
	s_cmp_eq_u32 s20, 28
	s_cselect_b32 s57, s47, s23
	s_cselect_b32 s56, vcc_lo, s22
	s_cselect_b32 s23, s49, s77
	s_cselect_b32 s22, vcc_hi, s71
	s_add_i32 s5, s65, 0x10000
	s_add_i32 s4, s65, 0x14000
.LBB0_216:
	ds_read_b128 v[144:147], v152
	ds_read_b128 v[148:151], v152 offset:1024
	ds_read_b128 v[168:171], v152 offset:2048
	ds_read_b128 v[172:175], v152 offset:3072
	ds_read_b128 v[176:179], v153
	ds_read_b128 v[180:183], v153 offset:1024
	ds_read_b128 v[184:187], v153 offset:2048
	ds_read_b128 v[188:191], v153 offset:3072
	ds_read_b128 v[212:215], v157
	ds_read_b128 v[216:219], v157 offset:1024
	ds_read_b128 v[220:223], v157 offset:2048
	ds_read_b128 v[224:227], v157 offset:3072
	ds_read_b128 v[228:231], v157 offset:4096
	ds_read_b128 v[232:235], v157 offset:5120
	ds_read_b128 v[236:239], v157 offset:6144
	s_add_i32 m0, s66, 0xc000
	ds_read_b128 v[240:243], v157 offset:7168
	global_load_lds_dwordx4 v140, s[54:55]
	s_add_i32 m0, s66, 0xe000
	s_nop 0
	global_load_lds_dwordx4 v142, s[54:55]
	s_waitcnt vmcnt(8)
	s_waitcnt lgkmcnt(0)
	s_barrier
	v_mfma_f32_16x16x32_bf16 v[126:129], v[144:147], v[212:215], v[126:129]
	v_mfma_f32_16x16x32_bf16 v[126:129], v[148:151], v[216:219], v[126:129]
	s_add_u32 s34, s22, 0x80000
	s_addc_u32 s35, s23, 0
	v_mfma_f32_16x16x32_bf16 v[118:121], v[168:171], v[212:215], v[118:121]
	v_mfma_f32_16x16x32_bf16 v[118:121], v[172:175], v[216:219], v[118:121]
	v_mfma_f32_16x16x32_bf16 v[130:133], v[176:179], v[212:215], v[130:133]
	v_mfma_f32_16x16x32_bf16 v[130:133], v[180:183], v[216:219], v[130:133]
	v_mfma_f32_16x16x32_bf16 v[122:125], v[184:187], v[212:215], v[122:125]
	v_mfma_f32_16x16x32_bf16 v[122:125], v[188:191], v[216:219], v[122:125]
	v_mfma_f32_16x16x32_bf16 v[106:109], v[184:187], v[220:223], v[106:109]
	v_mfma_f32_16x16x32_bf16 v[106:109], v[188:191], v[224:227], v[106:109]
	v_mfma_f32_16x16x32_bf16 v[114:117], v[176:179], v[220:223], v[114:117]
	v_mfma_f32_16x16x32_bf16 v[114:117], v[180:183], v[224:227], v[114:117]
	v_mfma_f32_16x16x32_bf16 v[102:105], v[168:171], v[220:223], v[102:105]
	v_mfma_f32_16x16x32_bf16 v[102:105], v[172:175], v[224:227], v[102:105]
	v_mfma_f32_16x16x32_bf16 v[110:113], v[144:147], v[220:223], v[110:113]
	v_mfma_f32_16x16x32_bf16 v[110:113], v[148:151], v[224:227], v[110:113]
	v_mfma_f32_16x16x32_bf16 v[94:97], v[144:147], v[228:231], v[94:97]
	v_mfma_f32_16x16x32_bf16 v[94:97], v[148:151], v[232:235], v[94:97]
	v_mfma_f32_16x16x32_bf16 v[86:89], v[168:171], v[228:231], v[86:89]
	v_mfma_f32_16x16x32_bf16 v[86:89], v[172:175], v[232:235], v[86:89]
	v_mfma_f32_16x16x32_bf16 v[98:101], v[176:179], v[228:231], v[98:101]
	v_mfma_f32_16x16x32_bf16 v[98:101], v[180:183], v[232:235], v[98:101]
	v_mfma_f32_16x16x32_bf16 v[90:93], v[184:187], v[228:231], v[90:93]
	v_mfma_f32_16x16x32_bf16 v[90:93], v[188:191], v[232:235], v[90:93]
	v_mfma_f32_16x16x32_bf16 v[74:77], v[184:187], v[236:239], v[74:77]
	v_mfma_f32_16x16x32_bf16 v[74:77], v[188:191], v[240:243], v[74:77]
	v_mfma_f32_16x16x32_bf16 v[82:85], v[176:179], v[236:239], v[82:85]
	v_mfma_f32_16x16x32_bf16 v[82:85], v[180:183], v[240:243], v[82:85]
	v_mfma_f32_16x16x32_bf16 v[70:73], v[168:171], v[236:239], v[70:73]
	v_mfma_f32_16x16x32_bf16 v[70:73], v[172:175], v[240:243], v[70:73]
	v_mfma_f32_16x16x32_bf16 v[78:81], v[144:147], v[236:239], v[78:81]
	v_mfma_f32_16x16x32_bf16 v[78:81], v[148:151], v[240:243], v[78:81]
	s_barrier
	ds_read_b128 v[212:215], v157 offset:16384
	ds_read_b128 v[216:219], v157 offset:17408
	s_mov_b32 m0, s5
	ds_read_b128 v[220:223], v157 offset:18432
	global_load_lds_dwordx4 v4, s[22:23]
	s_add_i32 m0, s5, 0x2000
	ds_read_b128 v[224:227], v157 offset:19456
	global_load_lds_dwordx4 v2, s[22:23]
	s_mov_b32 m0, s4
	ds_read_b128 v[228:231], v157 offset:20480
	global_load_lds_dwordx4 v4, s[34:35]
	s_add_i32 m0, s4, 0x2000
	ds_read_b128 v[232:235], v157 offset:21504
	global_load_lds_dwordx4 v2, s[34:35]
	s_mov_b32 m0, s66
	ds_read_b128 v[236:239], v157 offset:22528
	global_load_lds_dwordx4 v136, s[56:57]
	s_mov_b32 m0, s67
	ds_read_b128 v[240:243], v157 offset:23552
	global_load_lds_dwordx4 v134, s[56:57]
	s_waitcnt vmcnt(8)
	s_waitcnt lgkmcnt(0)
	s_barrier
; #define PG8_STAGE(bufoff, gbase, voff) do { _Pragma("unroll") for (int _i = 0; _i < 2; ++_i) \
;         __builtin_amdgcn_global_load_lds((const unsigned*)((const char*)(gbase) + (voff)[_i]), (PG8_LAS unsigned*)(lds + (bufoff) + ldsw + _i * 8192), 16, 0, 0); } while (0)
; #define PG8_LDA(dst, b, h) do { _Pragma("unroll") for (int m = 0; m < 4; ++m) _Pragma("unroll") for (int k = 0; k < 2; ++k) dst[m][k] = *(const PG8_LAS bf16x8*)(lds + PG8_SA(b, h) + aoff + m * 2048 + k * 1024); } while (0)
; #define PG8_LDB(dst, b, h) do { _Pragma("unroll") for (int n = 0; n < 2; ++n) _Pragma("unroll") for (int k = 0; k < 2; ++k) dst[n][k] = *(const PG8_LAS bf16x8*)(lds + PG8_SB(b, h) + boff + n * 2048 + k * 1024); } while (0)
; #define PG8_MMA(ai, bj, At, Bt) do { __builtin_amdgcn_s_setprio(1); _Pragma("unroll") for (int m = 0; m < 4; ++m) _Pragma("unroll") for (int n = 0; n < 2; ++n) _Pragma("unroll") for (int k = 0; k < 2; ++k) \
;         acc[ai][bj][m][n] = __builtin_amdgcn_mfma_f32_16x16x32_bf16(Bt[n][k], At[m][k], acc[ai][bj][m][n], 0, 0, 0); __builtin_amdgcn_s_setprio(0); } while (0)
; #define PG8_WAIT_V(n) asm volatile("s_waitcnt vmcnt(" #n ")" ::: "memory")
; #define PG8_WAIT_L(n) asm volatile("s_waitcnt lgkmcnt(" #n ")" ::: "memory")
; #define PG8_BAR __builtin_amdgcn_s_barrier()
; #define PG8_SCHED __builtin_amdgcn_sched_barrier(0)
; template <class Epi, class Sched, bool ALIGN_EPI = false, bool SP2 = false>
; __device__ __forceinline__ void gemm_phase(PG8_LAS unsigned char* lds, const Gemm g, const Sched& S, const Epi& E) {
;     ...
;             PG8_WAIT_V(8); PG8_WAIT_L(0); PG8_BAR; PG8_MMA(1, 0, At, B0); PG8_MMA(1, 1, At, B1); PG8_BAR; PG8_SCHED;
;             PG8_LDB(B0, 1, 0); PG8_LDB(B1, 1, 1); PG8_SCHED; PG8_LDA(At, 1, 0); PG8_STAGE(PG8_SA(0, 1), a2 + hstep, voffA);
;             PG8_WAIT_V(8); PG8_WAIT_L(0); PG8_BAR; PG8_MMA(0, 0, At, B0); PG8_MMA(0, 1, At, B1); PG8_BAR; PG8_SCHED;
;             PG8_LDA(At, 1, 1); PG8_STAGE(PG8_SB(1, 0), b3, voffB); PG8_STAGE(PG8_SB(1, 1), b3 + hstep, voffB); PG8_STAGE(PG8_SA(1, 0), a3, voffA);
	v_mfma_f32_16x16x32_bf16 v[62:65], v[144:147], v[212:215], v[62:65]
	v_mfma_f32_16x16x32_bf16 v[62:65], v[148:151], v[216:219], v[62:65]
	s_add_u32 s34, s56, 0x80000
	s_addc_u32 s35, s57, 0
	v_mfma_f32_16x16x32_bf16 v[54:57], v[168:171], v[212:215], v[54:57]
	v_mfma_f32_16x16x32_bf16 v[54:57], v[172:175], v[216:219], v[54:57]
	s_add_i32 s4, s65, 0x18000
	s_add_i32 s5, s65, 0x1c000
	v_mfma_f32_16x16x32_bf16 v[66:69], v[176:179], v[212:215], v[66:69]
	v_mfma_f32_16x16x32_bf16 v[66:69], v[180:183], v[216:219], v[66:69]
	v_mfma_f32_16x16x32_bf16 v[58:61], v[184:187], v[212:215], v[58:61]
	v_mfma_f32_16x16x32_bf16 v[58:61], v[188:191], v[216:219], v[58:61]
	v_mfma_f32_16x16x32_bf16 v[42:45], v[184:187], v[220:223], v[42:45]
	v_mfma_f32_16x16x32_bf16 v[42:45], v[188:191], v[224:227], v[42:45]
	v_mfma_f32_16x16x32_bf16 v[50:53], v[176:179], v[220:223], v[50:53]
	v_mfma_f32_16x16x32_bf16 v[50:53], v[180:183], v[224:227], v[50:53]
	v_mfma_f32_16x16x32_bf16 v[38:41], v[168:171], v[220:223], v[38:41]
	v_mfma_f32_16x16x32_bf16 v[38:41], v[172:175], v[224:227], v[38:41]
	v_mfma_f32_16x16x32_bf16 v[46:49], v[144:147], v[220:223], v[46:49]
	v_mfma_f32_16x16x32_bf16 v[46:49], v[148:151], v[224:227], v[46:49]
	v_mfma_f32_16x16x32_bf16 v[30:33], v[144:147], v[228:231], v[30:33]
	v_mfma_f32_16x16x32_bf16 v[30:33], v[148:151], v[232:235], v[30:33]
	v_mfma_f32_16x16x32_bf16 v[22:25], v[168:171], v[228:231], v[22:25]
	v_mfma_f32_16x16x32_bf16 v[22:25], v[172:175], v[232:235], v[22:25]
	v_mfma_f32_16x16x32_bf16 v[34:37], v[176:179], v[228:231], v[34:37]
	v_mfma_f32_16x16x32_bf16 v[34:37], v[180:183], v[232:235], v[34:37]
	v_mfma_f32_16x16x32_bf16 v[26:29], v[184:187], v[228:231], v[26:29]
	v_mfma_f32_16x16x32_bf16 v[26:29], v[188:191], v[232:235], v[26:29]
	v_mfma_f32_16x16x32_bf16 v[10:13], v[184:187], v[236:239], v[10:13]
	v_mfma_f32_16x16x32_bf16 v[10:13], v[188:191], v[240:243], v[10:13]
	v_mfma_f32_16x16x32_bf16 v[18:21], v[176:179], v[236:239], v[18:21]
	v_mfma_f32_16x16x32_bf16 v[18:21], v[180:183], v[240:243], v[18:21]
	v_mfma_f32_16x16x32_bf16 v[6:9], v[168:171], v[236:239], v[6:9]
	v_mfma_f32_16x16x32_bf16 v[6:9], v[172:175], v[240:243], v[6:9]
	v_mfma_f32_16x16x32_bf16 v[14:17], v[144:147], v[236:239], v[14:17]
	v_mfma_f32_16x16x32_bf16 v[14:17], v[148:151], v[240:243], v[14:17]
	s_barrier
	ds_read_b128 v[144:147], v192
	ds_read_b128 v[148:151], v192 offset:1024
	ds_read_b128 v[168:171], v192 offset:2048
	ds_read_b128 v[172:175], v192 offset:3072
	ds_read_b128 v[176:179], v193
	ds_read_b128 v[180:183], v193 offset:1024
	ds_read_b128 v[184:187], v193 offset:2048
	ds_read_b128 v[188:191], v193 offset:3072
	ds_read_b128 v[212:215], v157 offset:32768
	ds_read_b128 v[216:219], v157 offset:33792
	ds_read_b128 v[220:223], v157 offset:34816
	ds_read_b128 v[224:227], v157 offset:35840
	ds_read_b128 v[228:231], v157 offset:36864
	ds_read_b128 v[232:235], v157 offset:37888
	s_mov_b32 m0, s60
	ds_read_b128 v[236:239], v157 offset:38912
	global_load_lds_dwordx4 v136, s[34:35]
	s_mov_b32 m0, s2
	ds_read_b128 v[240:243], v157 offset:39936
	global_load_lds_dwordx4 v134, s[34:35]
	s_waitcnt vmcnt(8)
	s_waitcnt lgkmcnt(0)
	s_barrier
	v_mfma_f32_16x16x32_bf16 v[126:129], v[144:147], v[212:215], v[126:129]
	v_mfma_f32_16x16x32_bf16 v[126:129], v[148:151], v[216:219], v[126:129]
	s_add_u32 s34, s22, 0x80080
	s_addc_u32 s35, s23, 0
	v_mfma_f32_16x16x32_bf16 v[118:121], v[168:171], v[212:215], v[118:121]
	v_mfma_f32_16x16x32_bf16 v[118:121], v[172:175], v[216:219], v[118:121]
	v_mfma_f32_16x16x32_bf16 v[130:133], v[176:179], v[212:215], v[130:133]
	v_mfma_f32_16x16x32_bf16 v[130:133], v[180:183], v[216:219], v[130:133]
	v_mfma_f32_16x16x32_bf16 v[122:125], v[184:187], v[212:215], v[122:125]
	v_mfma_f32_16x16x32_bf16 v[122:125], v[188:191], v[216:219], v[122:125]
	v_mfma_f32_16x16x32_bf16 v[106:109], v[184:187], v[220:223], v[106:109]
	v_mfma_f32_16x16x32_bf16 v[106:109], v[188:191], v[224:227], v[106:109]
	v_mfma_f32_16x16x32_bf16 v[114:117], v[176:179], v[220:223], v[114:117]
	v_mfma_f32_16x16x32_bf16 v[114:117], v[180:183], v[224:227], v[114:117]
	v_mfma_f32_16x16x32_bf16 v[102:105], v[168:171], v[220:223], v[102:105]
	v_mfma_f32_16x16x32_bf16 v[102:105], v[172:175], v[224:227], v[102:105]
	v_mfma_f32_16x16x32_bf16 v[110:113], v[144:147], v[220:223], v[110:113]
	v_mfma_f32_16x16x32_bf16 v[110:113], v[148:151], v[224:227], v[110:113]
	v_mfma_f32_16x16x32_bf16 v[94:97], v[144:147], v[228:231], v[94:97]
	v_mfma_f32_16x16x32_bf16 v[94:97], v[148:151], v[232:235], v[94:97]
	v_mfma_f32_16x16x32_bf16 v[86:89], v[168:171], v[228:231], v[86:89]
	v_mfma_f32_16x16x32_bf16 v[86:89], v[172:175], v[232:235], v[86:89]
	v_mfma_f32_16x16x32_bf16 v[98:101], v[176:179], v[228:231], v[98:101]
	v_mfma_f32_16x16x32_bf16 v[98:101], v[180:183], v[232:235], v[98:101]
	v_mfma_f32_16x16x32_bf16 v[90:93], v[184:187], v[228:231], v[90:93]
	v_mfma_f32_16x16x32_bf16 v[90:93], v[188:191], v[232:235], v[90:93]
	v_mfma_f32_16x16x32_bf16 v[74:77], v[184:187], v[236:239], v[74:77]
	v_mfma_f32_16x16x32_bf16 v[74:77], v[188:191], v[240:243], v[74:77]
	v_mfma_f32_16x16x32_bf16 v[82:85], v[176:179], v[236:239], v[82:85]
	v_mfma_f32_16x16x32_bf16 v[82:85], v[180:183], v[240:243], v[82:85]
	v_mfma_f32_16x16x32_bf16 v[70:73], v[168:171], v[236:239], v[70:73]
	v_mfma_f32_16x16x32_bf16 v[70:73], v[172:175], v[240:243], v[70:73]
	v_mfma_f32_16x16x32_bf16 v[78:81], v[144:147], v[236:239], v[78:81]
	v_mfma_f32_16x16x32_bf16 v[78:81], v[148:151], v[240:243], v[78:81]
	s_barrier
; #define PG8_STAGE(bufoff, gbase, voff) do { _Pragma("unroll") for (int _i = 0; _i < 2; ++_i) \
;         __builtin_amdgcn_global_load_lds((const unsigned*)((const char*)(gbase) + (voff)[_i]), (PG8_LAS unsigned*)(lds + (bufoff) + ldsw + _i * 8192), 16, 0, 0); } while (0)
; #define PG8_LDA(dst, b, h) do { _Pragma("unroll") for (int m = 0; m < 4; ++m) _Pragma("unroll") for (int k = 0; k < 2; ++k) dst[m][k] = *(const PG8_LAS bf16x8*)(lds + PG8_SA(b, h) + aoff + m * 2048 + k * 1024); } while (0)
; #define PG8_LDB(dst, b, h) do { _Pragma("unroll") for (int n = 0; n < 2; ++n) _Pragma("unroll") for (int k = 0; k < 2; ++k) dst[n][k] = *(const PG8_LAS bf16x8*)(lds + PG8_SB(b, h) + boff + n * 2048 + k * 1024); } while (0)
; template <class Epi, class Sched, bool ALIGN_EPI = false, bool SP2 = false>
; __device__ __forceinline__ void gemm_phase(PG8_LAS unsigned char* lds, const Gemm g, const Sched& S, const Epi& E) {
;     ...
;         for (int t = 0; t < nt; t += 2) {
;             const bool last = (t == nt - 2);
;             const char* a1 = cA + (size_t)(t + 1) * kstep;
;             const char* a2 = last ? nA : cA + (size_t)(t + 2) * kstep; const char* b2 = last ? nB : cB + (size_t)(t + 2) * kstep;
;             const char* a3 = a2 + kstep; const char* b3 = b2 + kstep;
;             if (last && has_next) S.a_ready(nxt);
;             if constexpr (SP2) {
;             PG8_LDB(B0, 0, 0); PG8_LDB(B1, 0, 1); PG8_SCHED; PG8_LDA(At, 0, 0); PG8_STAGE(PG8_SA(1, 1), a1 + hstep, voffA);
;             PG8_WAIT_V(8); PG8_WAIT_L(0); PG8_BAR; PG8_MMA(0, 0, At, B0); PG8_MMA(0, 1, At, B1); PG8_BAR; PG8_SCHED;
;             PG8_LDA(At, 0, 1); PG8_STAGE(PG8_SB(0, 0), b2, voffB); PG8_STAGE(PG8_SB(0, 1), b2 + hstep, voffB); PG8_STAGE(PG8_SA(0, 0), a2, voffA);
;             PG8_WAIT_V(8); PG8_WAIT_L(0); PG8_BAR; PG8_MMA(1, 0, At, B0); PG8_MMA(1, 1, At, B1); PG8_BAR; PG8_SCHED;
;             PG8_LDB(B0, 1, 0); PG8_LDB(B1, 1, 1); PG8_SCHED; PG8_LDA(At, 1, 0); PG8_STAGE(PG8_SA(0, 1), a2 + hstep, voffA);
;             PG8_WAIT_V(8); PG8_WAIT_L(0); PG8_BAR; PG8_MMA(0, 0, At, B0); PG8_MMA(0, 1, At, B1); PG8_BAR; PG8_SCHED;
;             PG8_LDA(At, 1, 1); PG8_STAGE(PG8_SB(1, 0), b3, voffB); PG8_STAGE(PG8_SB(1, 1), b3 + hstep, voffB); PG8_STAGE(PG8_SA(1, 0), a3, voffA);
;             PG8_WAIT_V(8); PG8_WAIT_L(0); PG8_BAR; PG8_MMA(1, 0, At, B0); PG8_MMA(1, 1, At, B1); PG8_BAR; PG8_SCHED;
	ds_read_b128 v[212:215], v157 offset:49152
	ds_read_b128 v[216:219], v157 offset:50176
	s_add_i32 m0, s4, 0xffffff80
	ds_read_b128 v[220:223], v157 offset:51200
	global_load_lds_dwordx4 v4, s[22:23] offset:128
	s_add_i32 m0, s4, 0x1f80
	ds_read_b128 v[224:227], v157 offset:52224
	global_load_lds_dwordx4 v2, s[22:23] offset:128
	s_mov_b32 m0, s5
	ds_read_b128 v[228:231], v157 offset:53248
	global_load_lds_dwordx4 v4, s[34:35]
	s_add_i32 m0, s5, 0x2000
	ds_read_b128 v[232:235], v157 offset:54272
	global_load_lds_dwordx4 v2, s[34:35]
	s_add_i32 m0, s3, 0xffffff80
	ds_read_b128 v[236:239], v157 offset:55296
	global_load_lds_dwordx4 v136, s[56:57] offset:128
	s_add_i32 m0, s75, 0xffffff80
	ds_read_b128 v[240:243], v157 offset:56320
	global_load_lds_dwordx4 v134, s[56:57] offset:128
	s_waitcnt vmcnt(8)
	s_waitcnt lgkmcnt(0)
	s_barrier
	v_mfma_f32_16x16x32_bf16 v[62:65], v[144:147], v[212:215], v[62:65]
	v_mfma_f32_16x16x32_bf16 v[62:65], v[148:151], v[216:219], v[62:65]
	s_add_i32 s20, s20, 2
	s_add_u32 s54, s54, 0x100
	v_mfma_f32_16x16x32_bf16 v[54:57], v[168:171], v[212:215], v[54:57]
	v_mfma_f32_16x16x32_bf16 v[54:57], v[172:175], v[216:219], v[54:57]
	s_addc_u32 s55, s55, 0
	s_add_u32 s71, s71, 0x100
	v_mfma_f32_16x16x32_bf16 v[66:69], v[176:179], v[212:215], v[66:69]
	v_mfma_f32_16x16x32_bf16 v[66:69], v[180:183], v[216:219], v[66:69]
	s_addc_u32 s77, s77, 0
	s_add_u32 s22, s54, 0xfff80080
	v_mfma_f32_16x16x32_bf16 v[58:61], v[184:187], v[212:215], v[58:61]
	v_mfma_f32_16x16x32_bf16 v[58:61], v[188:191], v[216:219], v[58:61]
	s_addc_u32 s23, s55, -1
	s_cmp_eq_u32 s20, 28
	v_mfma_f32_16x16x32_bf16 v[42:45], v[184:187], v[220:223], v[42:45]
	v_mfma_f32_16x16x32_bf16 v[42:45], v[188:191], v[224:227], v[42:45]
	s_cselect_b32 s57, s47, s23
	s_cselect_b32 s56, vcc_lo, s22
	v_mfma_f32_16x16x32_bf16 v[50:53], v[176:179], v[220:223], v[50:53]
	v_mfma_f32_16x16x32_bf16 v[50:53], v[180:183], v[224:227], v[50:53]
	s_cselect_b32 s23, s49, s77
	s_cselect_b32 s22, vcc_hi, s71
	v_mfma_f32_16x16x32_bf16 v[38:41], v[168:171], v[220:223], v[38:41]
	v_mfma_f32_16x16x32_bf16 v[38:41], v[172:175], v[224:227], v[38:41]
	s_add_i32 s5, s65, 0x10000
	s_add_i32 s4, s65, 0x14000
	v_mfma_f32_16x16x32_bf16 v[46:49], v[144:147], v[220:223], v[46:49]
	v_mfma_f32_16x16x32_bf16 v[46:49], v[148:151], v[224:227], v[46:49]
	s_cmp_gt_u32 s20, 29
	v_mfma_f32_16x16x32_bf16 v[30:33], v[144:147], v[228:231], v[30:33]
	v_mfma_f32_16x16x32_bf16 v[30:33], v[148:151], v[232:235], v[30:33]
	v_mfma_f32_16x16x32_bf16 v[22:25], v[168:171], v[228:231], v[22:25]
	v_mfma_f32_16x16x32_bf16 v[22:25], v[172:175], v[232:235], v[22:25]
	v_mfma_f32_16x16x32_bf16 v[34:37], v[176:179], v[228:231], v[34:37]
	v_mfma_f32_16x16x32_bf16 v[34:37], v[180:183], v[232:235], v[34:37]
	v_mfma_f32_16x16x32_bf16 v[26:29], v[184:187], v[228:231], v[26:29]
	v_mfma_f32_16x16x32_bf16 v[26:29], v[188:191], v[232:235], v[26:29]
	v_mfma_f32_16x16x32_bf16 v[10:13], v[184:187], v[236:239], v[10:13]
	v_mfma_f32_16x16x32_bf16 v[10:13], v[188:191], v[240:243], v[10:13]
	v_mfma_f32_16x16x32_bf16 v[18:21], v[176:179], v[236:239], v[18:21]
	v_mfma_f32_16x16x32_bf16 v[18:21], v[180:183], v[240:243], v[18:21]
	v_mfma_f32_16x16x32_bf16 v[6:9], v[168:171], v[236:239], v[6:9]
	v_mfma_f32_16x16x32_bf16 v[6:9], v[172:175], v[240:243], v[6:9]
	v_mfma_f32_16x16x32_bf16 v[14:17], v[144:147], v[236:239], v[14:17]
	v_mfma_f32_16x16x32_bf16 v[14:17], v[148:151], v[240:243], v[14:17]
	s_barrier
	s_cbranch_scc0 .LBB0_216
	s_and_b64 vcc, exec, s[44:45]
	s_movk_i32 s77, 0x6000
	s_mov_b32 s71, 0x44800000
	s_cbranch_vccz .LBB0_219
	s_barrier
